# norm phase: per-row wave_sum butterflies (6 dependent ds_bpermute round trips) replaced by DPP scan + readlane, on top of v16
# speedup vs baseline: 1.0074x; 1.0074x over previous
; DI unsigned pk2(float lo, float hi) { f32x2 v = {lo, hi}; bf16x2_t b = __builtin_convertvector(v, bf16x2_t); return __builtin_bit_cast(unsigned, b); }
; DI void norm_phase(const float* xin, const float* gain, const float* mods_ls, bf16_t* h, int wave, int lane) {
;     ...
;         for (int r = 0; r < 8; ++r) {
;             const float* xr = xin + (size_t)(m0 + r) * DM + 4 * lane;
;             f32x4 v[4]; float ss = 0.f;
; #pragma unroll
;             for (int j = 0; j < 4; ++j) { v[j] = *(const f32x4*)(xr + 256 * j); ss += (v[j].x * v[j].x + v[j].y * v[j].y) + (v[j].z * v[j].z + v[j].w * v[j].w); }
;             const float rstd = rsqrtf(wave_sum(ss) * (1.0f / DM) + EPS);
;             bf16_t* hr = h + (size_t)(m0 + r) * DM + 4 * lane;
; #pragma unroll
;             for (int j = 0; j < 4; ++j) { const f32x4 o = v[j] * rstd * gsc[j] + sh[j]; u32x2 w; w.x = pk2(o.x, o.y); w.y = pk2(o.z, o.w); *(u32x2*)(hr + 256 * j) = w; }
.LBB0_161:
	global_load_dwordx4 v[58:61], v[30:31], off offset:-3072
	global_load_dwordx4 v[62:65], v[30:31], off offset:-2048
	global_load_dwordx4 v[66:69], v[30:31], off
	global_load_dwordx4 v[70:73], v[30:31], off offset:-1024
	v_lshl_add_u64 v[74:75], v[28:29], 0, s[2:3]
	s_mov_b32 s1, 0xb240000
	v_add_co_u32_e32 v74, vcc, s1, v74
	s_ashr_i32 s5, s4, 31
	s_nop 0
	v_addc_co_u32_e32 v75, vcc, 0, v75, vcc
	s_lshl_b64 s[8:9], s[4:5], 12
	v_lshl_add_u64 v[76:77], v[18:19], 0, s[8:9]
	s_mov_b64 s[8:9], 0x2000
	v_lshl_add_u64 v[30:31], v[30:31], 0, s[8:9]
	s_lshl_b64 s[8:9], s[4:5], 11
	s_add_i32 s4, s4, 2
	s_add_u32 s2, s2, 0x1000
	s_addc_u32 s3, s3, 0
	s_cmpk_eq_i32 s2, 0x4000
	s_waitcnt vmcnt(3)
	v_pk_mul_f32 v[78:79], v[60:61], v[60:61]
	v_pk_mul_f32 v[80:81], v[58:59], v[58:59]
	s_waitcnt vmcnt(2)
	v_pk_mul_f32 v[82:83], v[64:65], v[64:65]
	v_pk_mul_f32 v[84:85], v[62:63], v[62:63]
	v_pk_mov_b32 v[90:91], v[80:81], v[78:79] op_sel:[1,0]
	v_mov_b32_e32 v81, v79
	v_pk_mov_b32 v[78:79], v[84:85], v[82:83] op_sel:[1,0]
	v_mov_b32_e32 v85, v83
	s_waitcnt vmcnt(1)
	v_mul_f32_e32 v89, v67, v67
	s_waitcnt vmcnt(0)
	v_mul_f32_e32 v86, v71, v71
	v_mul_f32_e32 v88, v73, v73
	v_pk_add_f32 v[80:81], v[90:91], v[80:81]
	v_pk_add_f32 v[78:79], v[78:79], v[84:85]
	v_mul_f32_e32 v57, v66, v66
	v_mul_f32_e32 v92, v68, v68
	v_mul_f32_e32 v93, v69, v69
	v_pk_fma_f32 v[82:83], v[70:71], v[70:71], v[86:87] op_sel_hi:[1,1,0]
	v_pk_fma_f32 v[86:87], v[72:73], v[72:73], v[88:89] op_sel_hi:[1,1,0]
	v_pk_add_f32 v[80:81], v[80:81], v[80:81] op_sel:[0,1] op_sel_hi:[1,0]
	v_pk_add_f32 v[78:79], v[78:79], v[78:79] op_sel:[0,1] op_sel_hi:[1,0]
	v_mov_b32_e32 v83, v92
	v_mov_b32_e32 v87, v93
	v_mov_b32_e32 v81, v57
	v_mov_b32_e32 v79, v89
	v_pk_add_f32 v[82:83], v[82:83], v[86:87]
	v_pk_add_f32 v[78:79], v[80:81], v[78:79]
	s_nop 0
	v_pk_add_f32 v[78:79], v[78:79], v[82:83]
	s_nop 0
	v_add_f32_e32 v57, v78, v79
	s_nop 1
	v_add_f32_dpp v57, v57, v57 row_shr:1 row_mask:0xf bank_mask:0xf bound_ctrl:0
	s_nop 1
	v_add_f32_dpp v57, v57, v57 row_shr:2 row_mask:0xf bank_mask:0xf bound_ctrl:0
	s_nop 1
	v_add_f32_dpp v57, v57, v57 row_shr:4 row_mask:0xf bank_mask:0xf bound_ctrl:0
	s_nop 1
	v_add_f32_dpp v57, v57, v57 row_shr:8 row_mask:0xf bank_mask:0xf bound_ctrl:0
	s_nop 1
	v_add_f32_dpp v57, v57, v57 row_bcast:15 row_mask:0xa bank_mask:0xf
	s_nop 1
	v_add_f32_dpp v57, v57, v57 row_bcast:31 row_mask:0xc bank_mask:0xf
	s_nop 1
	v_readlane_b32 s1, v57, 63
	s_nop 3
	v_mov_b32_e32 v57, s1
	v_fmamk_f32 v57, v57, 0x3a800000, v152
	v_mul_f32_e32 v78, 0x4b800000, v57
	v_cmp_gt_f32_e32 vcc, s91, v57
	s_nop 1
	v_cndmask_b32_e32 v57, v57, v78, vcc
	v_rsq_f32_e32 v57, v57
	s_nop 0
	v_mul_f32_e32 v78, 0x45800000, v57
	v_cndmask_b32_e32 v78, v57, v78, vcc
	v_pk_mul_f32 v[58:59], v[58:59], v[78:79] op_sel_hi:[1,0]
	v_pk_mul_f32 v[60:61], v[60:61], v[78:79] op_sel_hi:[1,0]
	v_pk_mul_f32 v[62:63], v[62:63], v[78:79] op_sel_hi:[1,0]
	v_pk_mul_f32 v[64:65], v[64:65], v[78:79] op_sel_hi:[1,0]
	v_pk_mul_f32 v[70:71], v[70:71], v[78:79] op_sel_hi:[1,0]
	v_pk_mul_f32 v[72:73], v[72:73], v[78:79] op_sel_hi:[1,0]
	v_pk_mul_f32 v[66:67], v[66:67], v[78:79] op_sel_hi:[1,0]
	v_pk_mul_f32 v[68:69], v[68:69], v[78:79] op_sel_hi:[1,0]
	v_pk_fma_f32 v[60:61], v[32:33], v[60:61], v[4:5]
	v_pk_fma_f32 v[58:59], v[34:35], v[58:59], v[2:3]
	v_pk_fma_f32 v[64:65], v[36:37], v[64:65], v[8:9]
	v_pk_fma_f32 v[62:63], v[38:39], v[62:63], v[6:7]
	v_pk_fma_f32 v[72:73], v[40:41], v[72:73], v[12:13]
	v_pk_fma_f32 v[70:71], v[42:43], v[70:71], v[10:11]
	v_pk_fma_f32 v[68:69], v[44:45], v[68:69], v[16:17]
	v_pk_fma_f32 v[66:67], v[46:47], v[66:67], v[14:15]
	v_cvt_pk_bf16_f32 v58, v58, v59
	v_cvt_pk_bf16_f32 v59, v60, v61
	v_cvt_pk_bf16_f32 v60, v62, v63
	v_cvt_pk_bf16_f32 v61, v64, v65
	v_cvt_pk_bf16_f32 v62, v70, v71
	v_cvt_pk_bf16_f32 v63, v72, v73
	v_cvt_pk_bf16_f32 v64, v66, v67
	v_cvt_pk_bf16_f32 v65, v68, v69
	global_store_dwordx2 v[74:75], v[58:59], off
	global_store_dwordx2 v[74:75], v[60:61], off offset:512
	global_store_dwordx2 v[74:75], v[62:63], off offset:1024
	global_store_dwordx2 v[74:75], v[64:65], off offset:1536
	global_load_dwordx4 v[58:61], v[76:77], off
	s_nop 0
	global_load_dwordx4 v[62:65], v[76:77], off offset:1024
	global_load_dwordx4 v[66:69], v[76:77], off offset:2048
	global_load_dwordx4 v[70:73], v[76:77], off offset:3072
	v_lshl_add_u64 v[74:75], v[20:21], 0, s[8:9]
	s_waitcnt vmcnt(3)
; DI unsigned pk2(float lo, float hi) { f32x2 v = {lo, hi}; bf16x2_t b = __builtin_convertvector(v, bf16x2_t); return __builtin_bit_cast(unsigned, b); }
; DI void norm_phase(const float* xin, const float* gain, const float* mods_ls, bf16_t* h, int wave, int lane) {
;     ...
;     for (int blk = gw; blk < T / 8; blk += ngw) {
;         const int m0 = blk * 8, b = m0 >> 12;
;         const float* shift = mods_ls + (size_t)b * 9216; const float* scale = shift + 1024;
;         f32x4 gsc[4], sh[4];
; #pragma unroll
;         for (int j = 0; j < 4; ++j) { const int c = 4 * lane + 256 * j; gsc[j] = *(const f32x4*)(gain + c) * (*(const f32x4*)(scale + c) + 1.0f); sh[j] = *(const f32x4*)(shift + c); }
; #pragma unroll 2
;         for (int r = 0; r < 8; ++r) {
;             const float* xr = xin + (size_t)(m0 + r) * DM + 4 * lane;
;             f32x4 v[4]; float ss = 0.f;
; #pragma unroll
;             for (int j = 0; j < 4; ++j) { v[j] = *(const f32x4*)(xr + 256 * j); ss += (v[j].x * v[j].x + v[j].y * v[j].y) + (v[j].z * v[j].z + v[j].w * v[j].w); }
;             const float rstd = rsqrtf(wave_sum(ss) * (1.0f / DM) + EPS);
;             bf16_t* hr = h + (size_t)(m0 + r) * DM + 4 * lane;
; #pragma unroll
;             for (int j = 0; j < 4; ++j) { const f32x4 o = v[j] * rstd * gsc[j] + sh[j]; u32x2 w; w.x = pk2(o.x, o.y); w.y = pk2(o.z, o.w); *(u32x2*)(hr + 256 * j) = w; }
;         }
	v_pk_mul_f32 v[76:77], v[60:61], v[60:61]
	v_pk_mul_f32 v[78:79], v[58:59], v[58:59]
	s_waitcnt vmcnt(2)
	v_pk_mul_f32 v[80:81], v[64:65], v[64:65]
	v_pk_mul_f32 v[82:83], v[62:63], v[62:63]
	v_pk_mov_b32 v[88:89], v[78:79], v[76:77] op_sel:[1,0]
	v_mov_b32_e32 v79, v77
	v_pk_mov_b32 v[76:77], v[82:83], v[80:81] op_sel:[1,0]
	v_mov_b32_e32 v83, v81
	s_waitcnt vmcnt(0)
	v_mul_f32_e32 v87, v71, v71
	v_mul_f32_e32 v84, v67, v67
	v_mul_f32_e32 v86, v69, v69
	v_pk_add_f32 v[78:79], v[88:89], v[78:79]
	v_pk_add_f32 v[76:77], v[76:77], v[82:83]
	v_mul_f32_e32 v57, v70, v70
	v_mul_f32_e32 v90, v72, v72
	v_mul_f32_e32 v91, v73, v73
	v_pk_fma_f32 v[80:81], v[66:67], v[66:67], v[84:85] op_sel_hi:[1,1,0]
	v_pk_fma_f32 v[84:85], v[68:69], v[68:69], v[86:87] op_sel_hi:[1,1,0]
	v_pk_add_f32 v[78:79], v[78:79], v[78:79] op_sel:[0,1] op_sel_hi:[1,0]
	v_pk_add_f32 v[76:77], v[76:77], v[76:77] op_sel:[0,1] op_sel_hi:[1,0]
	v_mov_b32_e32 v81, v90
	v_mov_b32_e32 v85, v91
	v_mov_b32_e32 v79, v57
	v_mov_b32_e32 v77, v87
	v_pk_add_f32 v[80:81], v[80:81], v[84:85]
	v_pk_add_f32 v[76:77], v[78:79], v[76:77]
	s_nop 0
	v_pk_add_f32 v[76:77], v[76:77], v[80:81]
	s_nop 0
	v_add_f32_e32 v57, v76, v77
	s_nop 1
	v_add_f32_dpp v57, v57, v57 row_shr:1 row_mask:0xf bank_mask:0xf bound_ctrl:0
	s_nop 1
	v_add_f32_dpp v57, v57, v57 row_shr:2 row_mask:0xf bank_mask:0xf bound_ctrl:0
	s_nop 1
	v_add_f32_dpp v57, v57, v57 row_shr:4 row_mask:0xf bank_mask:0xf bound_ctrl:0
	s_nop 1
	v_add_f32_dpp v57, v57, v57 row_shr:8 row_mask:0xf bank_mask:0xf bound_ctrl:0
	s_nop 1
	v_add_f32_dpp v57, v57, v57 row_bcast:15 row_mask:0xa bank_mask:0xf
	s_nop 1
	v_add_f32_dpp v57, v57, v57 row_bcast:31 row_mask:0xc bank_mask:0xf
	s_nop 1
	v_readlane_b32 s1, v57, 63
	s_nop 3
	v_mov_b32_e32 v57, s1
	v_fmamk_f32 v57, v57, 0x3a800000, v152
	v_mul_f32_e32 v76, 0x4b800000, v57
	v_cmp_gt_f32_e32 vcc, s91, v57
	s_nop 1
	v_cndmask_b32_e32 v57, v57, v76, vcc
	v_rsq_f32_e32 v57, v57
	s_nop 0
	v_mul_f32_e32 v76, 0x45800000, v57
	v_cndmask_b32_e32 v76, v57, v76, vcc
	v_pk_mul_f32 v[58:59], v[58:59], v[76:77] op_sel_hi:[1,0]
	v_pk_mul_f32 v[60:61], v[60:61], v[76:77] op_sel_hi:[1,0]
	v_pk_mul_f32 v[62:63], v[62:63], v[76:77] op_sel_hi:[1,0]
	v_pk_mul_f32 v[64:65], v[64:65], v[76:77] op_sel_hi:[1,0]
	v_pk_mul_f32 v[66:67], v[66:67], v[76:77] op_sel_hi:[1,0]
	v_pk_mul_f32 v[68:69], v[68:69], v[76:77] op_sel_hi:[1,0]
	v_pk_mul_f32 v[70:71], v[70:71], v[76:77] op_sel_hi:[1,0]
	v_pk_mul_f32 v[72:73], v[72:73], v[76:77] op_sel_hi:[1,0]
	v_pk_fma_f32 v[60:61], v[32:33], v[60:61], v[4:5]
	v_pk_fma_f32 v[58:59], v[34:35], v[58:59], v[2:3]
	v_pk_fma_f32 v[64:65], v[36:37], v[64:65], v[8:9]
	v_pk_fma_f32 v[62:63], v[38:39], v[62:63], v[6:7]
	v_pk_fma_f32 v[68:69], v[40:41], v[68:69], v[12:13]
	v_pk_fma_f32 v[66:67], v[42:43], v[66:67], v[10:11]
	v_pk_fma_f32 v[72:73], v[44:45], v[72:73], v[16:17]
	v_pk_fma_f32 v[70:71], v[46:47], v[70:71], v[14:15]
	v_cvt_pk_bf16_f32 v58, v58, v59
	v_cvt_pk_bf16_f32 v59, v60, v61
	v_cvt_pk_bf16_f32 v60, v62, v63
	v_cvt_pk_bf16_f32 v61, v64, v65
	v_cvt_pk_bf16_f32 v62, v66, v67
	v_cvt_pk_bf16_f32 v63, v68, v69
	v_cvt_pk_bf16_f32 v64, v70, v71
	v_cvt_pk_bf16_f32 v65, v72, v73
	global_store_dwordx2 v[74:75], v[58:59], off
	global_store_dwordx2 v[74:75], v[60:61], off offset:512
	global_store_dwordx2 v[74:75], v[62:63], off offset:1024
	global_store_dwordx2 v[74:75], v[64:65], off offset:1536
	s_cbranch_scc0 .LBB0_161
	v_readlane_b32 s1, v254, 6
	s_add_i32 s6, s6, s1
	v_readlane_b32 s1, v254, 22
	s_add_i32 s7, s7, s1
	s_add_i32 s0, s0, s1
	s_cmpk_gt_i32 s6, 0x7ff
	s_cbranch_scc0 .LBB0_160
